# SwiGLU epilogue h stores with nt (P2,P11) so the 721 MB stream does not displace the GEMM operand panels in L2/MALL; on top of v2
# speedup vs baseline: 1.0081x; 1.0081x over previous
.LBB0_216:
	v_lshl_or_b32 v172, s92, 7, v155
	v_ashrrev_i32_e32 v173, 31, v172
	v_lshlrev_b64 v[146:147], 2, v[172:173]
	v_lshl_add_u64 v[152:153], s[80:81], 0, v[146:147]
	v_lshl_add_u64 v[146:147], s[36:37], 0, v[146:147]
	global_load_dwordx4 v[148:151], v[152:153], off
	global_load_dwordx4 v[160:163], v[152:153], off offset:16
	global_load_dwordx4 v[164:167], v[146:147], off
	global_load_dwordx4 v[168:171], v[146:147], off offset:16
	v_lshl_add_u32 v146, s82, 8, v1
	v_ashrrev_i32_e32 v147, 31, v146
	v_lshl_add_u64 v[152:153], v[146:147], 2, s[70:71]
	global_load_dword v174, v[152:153], off
	global_load_dword v192, v[152:153], off offset:64
	global_load_dword v193, v[152:153], off offset:128
	global_load_dword v194, v[152:153], off offset:192
	global_load_dword v195, v[152:153], off offset:512
	global_load_dword v196, v[152:153], off offset:576
	global_load_dword v197, v[152:153], off offset:640
	global_load_dword v198, v[152:153], off offset:704
	v_cvt_f32_i32_e32 v177, v127
	v_cvt_f32_i32_e32 v176, v126
	v_cvt_f32_i32_e32 v185, v119
	v_cvt_f32_i32_e32 v184, v118
	v_cvt_f32_i32_e32 v179, v129
	v_cvt_f32_i32_e32 v178, v128
	v_cvt_f32_i32_e32 v187, v121
	v_cvt_f32_i32_e32 v186, v120
	v_cvt_f32_i32_e32 v189, v115
	v_cvt_f32_i32_e32 v188, v114
	v_mov_b64_e32 v[114:115], s[38:39]
	v_cvt_f32_i32_e32 v191, v117
	v_cvt_f32_i32_e32 v190, v116
	v_mad_i64_i32 v[118:119], s[8:9], v146, s91, v[114:115]
	v_lshlrev_b64 v[116:117], 1, v[172:173]
	v_cvt_f32_i32_e32 v181, v123
	v_cvt_f32_i32_e32 v180, v122
	v_lshl_add_u64 v[172:173], v[118:119], 0, v[116:117]
	v_cvt_f32_i32_e32 v183, v125
	v_cvt_f32_i32_e32 v182, v124
	v_cvt_f32_i32_e32 v111, v111
	v_cvt_f32_i32_e32 v110, v110
	v_cvt_f32_i32_e32 v103, v103
	v_cvt_f32_i32_e32 v102, v102
	v_cvt_f32_i32_e32 v113, v113
	v_cvt_f32_i32_e32 v112, v112
	v_cvt_f32_i32_e32 v107, v107
	v_cvt_f32_i32_e32 v106, v106
	v_cvt_f32_i32_e32 v99, v99
	v_cvt_f32_i32_e32 v98, v98
	v_cvt_f32_i32_e32 v101, v101
	v_cvt_f32_i32_e32 v100, v100
	v_cvt_f32_i32_e32 v109, v109
	v_cvt_f32_i32_e32 v108, v108
	v_cvt_f32_i32_e32 v105, v105
	v_cvt_f32_i32_e32 v104, v104
	v_cvt_f32_i32_e32 v95, v95
	v_cvt_f32_i32_e32 v94, v94
	v_cvt_f32_i32_e32 v87, v87
	v_cvt_f32_i32_e32 v86, v86
	v_cvt_f32_i32_e32 v97, v97
	v_cvt_f32_i32_e32 v96, v96
	v_cvt_f32_i32_e32 v91, v91
	v_cvt_f32_i32_e32 v90, v90
	v_cvt_f32_i32_e32 v83, v83
	v_cvt_f32_i32_e32 v82, v82
	v_cvt_f32_i32_e32 v85, v85
	v_cvt_f32_i32_e32 v84, v84
	v_cvt_f32_i32_e32 v93, v93
	v_cvt_f32_i32_e32 v92, v92
	v_cvt_f32_i32_e32 v89, v89
	v_cvt_f32_i32_e32 v88, v88
	v_cvt_f32_i32_e32 v79, v79
	v_cvt_f32_i32_e32 v78, v78
	v_cvt_f32_i32_e32 v81, v81
	v_cvt_f32_i32_e32 v80, v80
	v_cvt_f32_i32_e32 v71, v71
	v_cvt_f32_i32_e32 v70, v70
	v_cvt_f32_i32_e32 v75, v75
	v_cvt_f32_i32_e32 v74, v74
	v_cvt_f32_i32_e32 v67, v67
	v_cvt_f32_i32_e32 v66, v66
	v_cvt_f32_i32_e32 v69, v69
	v_cvt_f32_i32_e32 v68, v68
	v_cvt_f32_i32_e32 v77, v77
	v_cvt_f32_i32_e32 v76, v76
	v_cvt_f32_i32_e32 v73, v73
	v_cvt_f32_i32_e32 v72, v72
	v_cvt_f32_i32_e32 v63, v63
	v_cvt_f32_i32_e32 v62, v62
	v_cvt_f32_i32_e32 v65, v65
	v_cvt_f32_i32_e32 v64, v64
	s_waitcnt vmcnt(0)
	v_pk_mul_f32 v[120:121], v[148:149], s[40:41] op_sel_hi:[1,0]
	v_pk_mul_f32 v[128:129], v[164:165], s[40:41] op_sel_hi:[1,0]
	v_pk_mul_f32 v[118:119], v[150:151], s[40:41] op_sel_hi:[1,0]
	v_pk_mul_f32 v[122:123], v[162:163], s[40:41] op_sel_hi:[1,0]
	v_pk_mul_f32 v[126:127], v[166:167], s[40:41] op_sel_hi:[1,0]
	v_pk_mul_f32 v[148:149], v[170:171], s[40:41] op_sel_hi:[1,0]
	v_pk_mul_f32 v[162:163], v[120:121], v[176:177]
	v_pk_mul_f32 v[170:171], v[128:129], v[184:185]
	v_pk_mul_f32 v[124:125], v[160:161], s[40:41] op_sel_hi:[1,0]
	v_pk_mul_f32 v[150:151], v[168:169], s[40:41] op_sel_hi:[1,0]
	v_pk_mul_f32 v[160:161], v[118:119], v[178:179]
	v_pk_mul_f32 v[168:169], v[126:127], v[186:187]
	v_pk_mul_f32 v[162:163], v[162:163], v[174:175] op_sel_hi:[1,0]
	v_pk_mul_f32 v[170:171], v[170:171], v[174:175] op_sel_hi:[1,0]
	v_pk_mul_f32 v[160:161], v[160:161], v[174:175] op_sel_hi:[1,0]
	v_pk_mul_f32 v[168:169], v[168:169], v[174:175] op_sel_hi:[1,0]
	v_mul_f32_e32 v147, v162, v170
	v_mul_f32_e32 v159, 0xbfb8aa3b, v162
	v_mul_f32_e32 v162, v163, v171
	v_mul_f32_e32 v163, 0xbfb8aa3b, v163
	v_mul_f32_e32 v168, v160, v168
	v_mul_f32_e32 v160, 0xbfb8aa3b, v160
	v_exp_f32_e32 v159, v159
	v_exp_f32_e32 v163, v163
	v_exp_f32_e32 v160, v160
	v_pk_mul_f32 v[164:165], v[122:123], v[182:183]
	v_pk_mul_f32 v[166:167], v[124:125], v[180:181]
	v_pk_mul_f32 v[176:177], v[148:149], v[190:191]
	v_pk_mul_f32 v[178:179], v[150:151], v[188:189]
	v_add_f32_e32 v159, 1.0, v159
	v_add_f32_e32 v163, 1.0, v163
	v_pk_mul_f32 v[164:165], v[164:165], v[174:175] op_sel_hi:[1,0]
	v_pk_mul_f32 v[166:167], v[166:167], v[174:175] op_sel_hi:[1,0]
	v_pk_mul_f32 v[176:177], v[176:177], v[174:175] op_sel_hi:[1,0]
	v_pk_mul_f32 v[174:175], v[178:179], v[174:175] op_sel_hi:[1,0]
	v_add_f32_e32 v160, 1.0, v160
	v_rcp_f32_e32 v159, v159
	v_rcp_f32_e32 v163, v163
	v_mul_f32_e32 v169, v161, v169
	v_mul_f32_e32 v161, 0xbfb8aa3b, v161
	v_mul_f32_e32 v170, v166, v174
	v_mul_f32_e32 v166, 0xbfb8aa3b, v166
	v_mul_f32_e32 v171, v167, v175
	v_mul_f32_e32 v167, 0xbfb8aa3b, v167
	v_rcp_f32_e32 v160, v160
	v_exp_f32_e32 v161, v161
	v_exp_f32_e32 v166, v166
	v_exp_f32_e32 v167, v167
	v_mul_f32_e32 v174, 0xbfb8aa3b, v164
	v_mul_f32_e32 v175, 0xbfb8aa3b, v165
	v_exp_f32_e32 v174, v174
	v_mul_f32_e32 v147, v147, v159
	v_mul_f32_e32 v159, v162, v163
	v_mul_f32_e32 v162, v168, v160
	v_cvt_pkrtz_f16_f32 v160, v147, v159
	v_exp_f32_e32 v147, v175
	v_add_f32_e32 v161, 1.0, v161
	v_add_f32_e32 v166, 1.0, v166
	v_add_f32_e32 v167, 1.0, v167
	v_rcp_f32_e32 v161, v161
	v_rcp_f32_e32 v166, v166
	v_rcp_f32_e32 v167, v167
	v_add_f32_e32 v159, 1.0, v174
	v_rcp_f32_e32 v159, v159
	v_add_f32_e32 v147, 1.0, v147
	v_rcp_f32_e32 v147, v147
	v_mul_f32_e32 v161, v169, v161
	v_mul_f32_e32 v163, v170, v166
	v_mul_f32_e32 v166, v171, v167
	v_cvt_pkrtz_f16_f32 v161, v162, v161
	v_cvt_pkrtz_f16_f32 v162, v163, v166
	v_mul_f32_e32 v163, v164, v176
	v_mul_f32_e32 v159, v163, v159
	v_mul_f32_e32 v163, v165, v177
	v_mul_f32_e32 v147, v163, v147
	v_cvt_pkrtz_f16_f32 v163, v159, v147
	global_store_dwordx4 v[172:173], v[160:163], off nt
	v_pk_mul_f32 v[110:111], v[120:121], v[110:111]
	v_pk_mul_f32 v[102:103], v[128:129], v[102:103]
	v_or_b32_e32 v160, 16, v146
	v_ashrrev_i32_e32 v161, 31, v160
	v_lshl_add_u64 v[162:163], v[160:161], 2, s[70:71]
	v_mov_b32_e32 v162, v192
	v_pk_mul_f32 v[112:113], v[118:119], v[112:113]
	v_pk_mul_f32 v[106:107], v[124:125], v[106:107]
	v_pk_mul_f32 v[100:101], v[148:149], v[100:101]
	v_pk_mul_f32 v[98:99], v[150:151], v[98:99]
	v_pk_mul_f32 v[108:109], v[122:123], v[108:109]
	v_pk_mul_f32 v[104:105], v[126:127], v[104:105]
	v_mad_i64_i32 v[160:161], s[8:9], v160, s91, v[114:115]
	v_lshl_add_u64 v[160:161], v[160:161], 0, v[116:117]
	v_pk_mul_f32 v[94:95], v[120:121], v[94:95]
	v_pk_mul_f32 v[86:87], v[128:129], v[86:87]
	v_pk_mul_f32 v[96:97], v[118:119], v[96:97]
	v_pk_mul_f32 v[90:91], v[124:125], v[90:91]
	v_pk_mul_f32 v[84:85], v[148:149], v[84:85]
	v_pk_mul_f32 v[82:83], v[150:151], v[82:83]
	v_pk_mul_f32 v[92:93], v[122:123], v[92:93]
	v_pk_mul_f32 v[88:89], v[126:127], v[88:89]
	v_pk_mul_f32 v[80:81], v[118:119], v[80:81]
	v_pk_mul_f32 v[78:79], v[120:121], v[78:79]
	v_pk_mul_f32 v[70:71], v[128:129], v[70:71]
	v_pk_mul_f32 v[74:75], v[124:125], v[74:75]
	v_pk_mul_f32 v[68:69], v[148:149], v[68:69]
	v_pk_mul_f32 v[66:67], v[150:151], v[66:67]
	v_pk_mul_f32 v[76:77], v[122:123], v[76:77]
	v_pk_mul_f32 v[72:73], v[126:127], v[72:73]
	v_cvt_f32_i32_e32 v59, v59
	v_cvt_f32_i32_e32 v58, v58
	v_cvt_f32_i32_e32 v61, v61
	v_cvt_f32_i32_e32 v60, v60
	v_cvt_f32_i32_e32 v55, v55
	v_cvt_f32_i32_e32 v54, v54
	v_cvt_f32_i32_e32 v57, v57
	v_cvt_f32_i32_e32 v56, v56
	v_cvt_f32_i32_e32 v51, v51
	v_cvt_f32_i32_e32 v50, v50
	v_cvt_f32_i32_e32 v53, v53
	v_cvt_f32_i32_e32 v52, v52
	v_pk_mul_f32 v[64:65], v[118:119], v[64:65]
	v_pk_mul_f32 v[62:63], v[120:121], v[62:63]
	v_pk_mul_f32 v[60:61], v[122:123], v[60:61]
	v_pk_mul_f32 v[58:59], v[124:125], v[58:59]
	v_pk_mul_f32 v[56:57], v[126:127], v[56:57]
	v_pk_mul_f32 v[54:55], v[128:129], v[54:55]
	v_pk_mul_f32 v[52:53], v[148:149], v[52:53]
	v_pk_mul_f32 v[50:51], v[150:151], v[50:51]
	v_cvt_f32_i32_e32 v47, v47
	v_cvt_f32_i32_e32 v46, v46
	v_cvt_f32_i32_e32 v49, v49
	v_cvt_f32_i32_e32 v48, v48
	v_cvt_f32_i32_e32 v43, v43
	v_cvt_f32_i32_e32 v42, v42
	v_cvt_f32_i32_e32 v45, v45
	v_cvt_f32_i32_e32 v44, v44
	v_cvt_f32_i32_e32 v39, v39
	v_cvt_f32_i32_e32 v38, v38
	v_cvt_f32_i32_e32 v41, v41
	v_cvt_f32_i32_e32 v40, v40
	v_cvt_f32_i32_e32 v35, v35
	v_cvt_f32_i32_e32 v34, v34
	v_cvt_f32_i32_e32 v37, v37
	v_cvt_f32_i32_e32 v36, v36
	v_pk_mul_f32 v[48:49], v[118:119], v[48:49]
	v_pk_mul_f32 v[46:47], v[120:121], v[46:47]
	v_pk_mul_f32 v[44:45], v[122:123], v[44:45]
	v_pk_mul_f32 v[42:43], v[124:125], v[42:43]
	v_pk_mul_f32 v[40:41], v[126:127], v[40:41]
	v_pk_mul_f32 v[38:39], v[128:129], v[38:39]
	v_pk_mul_f32 v[36:37], v[148:149], v[36:37]
	v_pk_mul_f32 v[34:35], v[150:151], v[34:35]
	v_cvt_f32_i32_e32 v31, v31
	v_cvt_f32_i32_e32 v30, v30
	v_cvt_f32_i32_e32 v33, v33
	v_cvt_f32_i32_e32 v32, v32
	v_cvt_f32_i32_e32 v27, v27
	v_cvt_f32_i32_e32 v26, v26
	v_cvt_f32_i32_e32 v29, v29
	v_cvt_f32_i32_e32 v28, v28
	v_cvt_f32_i32_e32 v23, v23
	v_cvt_f32_i32_e32 v22, v22
	v_pk_mul_f32 v[110:111], v[110:111], v[162:163] op_sel_hi:[1,0]
	v_pk_mul_f32 v[102:103], v[102:103], v[162:163] op_sel_hi:[1,0]
	v_pk_mul_f32 v[112:113], v[112:113], v[162:163] op_sel_hi:[1,0]
	v_pk_mul_f32 v[106:107], v[106:107], v[162:163] op_sel_hi:[1,0]
	v_pk_mul_f32 v[164:165], v[100:101], v[162:163] op_sel_hi:[1,0]
	v_pk_mul_f32 v[98:99], v[98:99], v[162:163] op_sel_hi:[1,0]
	v_mul_f32_e32 v100, v110, v102
	v_mul_f32_e32 v101, 0xbfb8aa3b, v110
	v_mul_f32_e32 v102, v111, v103
	v_mul_f32_e32 v103, 0xbfb8aa3b, v111
	v_mul_f32_e32 v110, 0xbfb8aa3b, v112
	v_mul_f32_e32 v111, 0xbfb8aa3b, v113
	v_mul_f32_e32 v98, v106, v98
	v_mul_f32_e32 v106, 0xbfb8aa3b, v106
	v_exp_f32_e32 v101, v101
	v_exp_f32_e32 v103, v103
	v_mul_f32_e32 v99, v107, v99
	v_mul_f32_e32 v107, 0xbfb8aa3b, v107
	v_exp_f32_e32 v110, v110
	v_exp_f32_e32 v111, v111
	v_exp_f32_e32 v106, v106
	v_exp_f32_e32 v107, v107
	v_pk_mul_f32 v[108:109], v[108:109], v[162:163] op_sel_hi:[1,0]
	v_pk_mul_f32 v[104:105], v[104:105], v[162:163] op_sel_hi:[1,0]
	v_add_f32_e32 v101, 1.0, v101
	v_add_f32_e32 v103, 1.0, v103
	v_mul_f32_e32 v104, v112, v104
	v_mul_f32_e32 v112, 0xbfb8aa3b, v108
	v_add_f32_e32 v110, 1.0, v110
	v_add_f32_e32 v111, 1.0, v111
	v_add_f32_e32 v106, 1.0, v106
	v_rcp_f32_e32 v101, v101
	v_rcp_f32_e32 v103, v103
	v_mul_f32_e32 v105, v113, v105
	v_mul_f32_e32 v113, 0xbfb8aa3b, v109
	v_exp_f32_e32 v112, v112
	v_add_f32_e32 v107, 1.0, v107
	v_rcp_f32_e32 v110, v110
	v_rcp_f32_e32 v111, v111
	v_rcp_f32_e32 v106, v106
	v_exp_f32_e32 v113, v113
	v_rcp_f32_e32 v107, v107
	v_mul_f32_e32 v100, v100, v101
	v_mul_f32_e32 v101, v102, v103
	v_mul_f32_e32 v102, v104, v110
	v_mul_f32_e32 v103, v105, v111
	v_mul_f32_e32 v104, v98, v106
	v_cvt_pkrtz_f16_f32 v98, v100, v101
	v_add_f32_e32 v101, 1.0, v112
	v_mul_f32_e32 v105, v99, v107
	v_cvt_pkrtz_f16_f32 v99, v102, v103
	v_rcp_f32_e32 v101, v101
	v_add_f32_e32 v102, 1.0, v113
	v_rcp_f32_e32 v102, v102
	v_mul_f32_e32 v103, v108, v164
	v_mul_f32_e32 v101, v103, v101
	v_mul_f32_e32 v103, v109, v165
	v_mul_f32_e32 v102, v103, v102
	v_cvt_pkrtz_f16_f32 v100, v104, v105
	v_cvt_pkrtz_f16_f32 v101, v101, v102
	global_store_dwordx4 v[160:161], v[98:101], off nt
	v_cvt_f32_i32_e32 v25, v25
	v_cvt_f32_i32_e32 v24, v24
	v_or_b32_e32 v98, 32, v146
	v_ashrrev_i32_e32 v99, 31, v98
	v_lshl_add_u64 v[100:101], v[98:99], 2, s[70:71]
	v_mov_b32_e32 v100, v193
	v_mad_i64_i32 v[98:99], s[8:9], v98, s91, v[114:115]
	v_lshl_add_u64 v[98:99], v[98:99], 0, v[116:117]
	v_cvt_f32_i32_e32 v19, v19
	v_cvt_f32_i32_e32 v18, v18
	v_cvt_f32_i32_e32 v21, v21
	v_cvt_f32_i32_e32 v20, v20
	v_pk_mul_f32 v[32:33], v[118:119], v[32:33]
	v_pk_mul_f32 v[30:31], v[120:121], v[30:31]
	v_pk_mul_f32 v[28:29], v[122:123], v[28:29]
	v_pk_mul_f32 v[26:27], v[124:125], v[26:27]
	v_pk_mul_f32 v[24:25], v[126:127], v[24:25]
	v_pk_mul_f32 v[22:23], v[128:129], v[22:23]
	v_pk_mul_f32 v[20:21], v[148:149], v[20:21]
	v_pk_mul_f32 v[18:19], v[150:151], v[18:19]
	v_cvt_f32_i32_e32 v15, v15
	v_cvt_f32_i32_e32 v14, v14
	v_cvt_f32_i32_e32 v17, v17
	v_cvt_f32_i32_e32 v16, v16
	v_cvt_f32_i32_e32 v11, v11
	v_cvt_f32_i32_e32 v10, v10
	v_cvt_f32_i32_e32 v13, v13
	v_cvt_f32_i32_e32 v12, v12
	v_cvt_f32_i32_e32 v7, v7
	v_cvt_f32_i32_e32 v6, v6
	v_cvt_f32_i32_e32 v9, v9
	v_cvt_f32_i32_e32 v8, v8
	v_cvt_f32_i32_e32 v3, v3
	v_cvt_f32_i32_e32 v2, v2
	v_cvt_f32_i32_e32 v5, v5
	v_cvt_f32_i32_e32 v4, v4
	v_pk_mul_f32 v[16:17], v[118:119], v[16:17]
	v_pk_mul_f32 v[14:15], v[120:121], v[14:15]
	v_pk_mul_f32 v[12:13], v[122:123], v[12:13]
	v_pk_mul_f32 v[10:11], v[124:125], v[10:11]
	v_pk_mul_f32 v[8:9], v[126:127], v[8:9]
	v_pk_mul_f32 v[6:7], v[128:129], v[6:7]
	v_pk_mul_f32 v[4:5], v[148:149], v[4:5]
	v_pk_mul_f32 v[2:3], v[150:151], v[2:3]
	s_andn2_b64 vcc, exec, s[2:3]
	s_mov_b64 s[2:3], -1
	v_pk_mul_f32 v[94:95], v[94:95], v[100:101] op_sel_hi:[1,0]
	v_pk_mul_f32 v[86:87], v[86:87], v[100:101] op_sel_hi:[1,0]
	v_pk_mul_f32 v[96:97], v[96:97], v[100:101] op_sel_hi:[1,0]
	v_pk_mul_f32 v[90:91], v[90:91], v[100:101] op_sel_hi:[1,0]
	v_pk_mul_f32 v[102:103], v[84:85], v[100:101] op_sel_hi:[1,0]
	v_pk_mul_f32 v[82:83], v[82:83], v[100:101] op_sel_hi:[1,0]
	v_mul_f32_e32 v84, v94, v86
	v_mul_f32_e32 v85, 0xbfb8aa3b, v94
	v_mul_f32_e32 v86, v95, v87
	v_mul_f32_e32 v87, 0xbfb8aa3b, v95
	v_mul_f32_e32 v94, 0xbfb8aa3b, v96
	v_mul_f32_e32 v82, v90, v82
	v_mul_f32_e32 v90, 0xbfb8aa3b, v90
	v_exp_f32_e32 v85, v85
	v_exp_f32_e32 v87, v87
	v_exp_f32_e32 v94, v94
	v_exp_f32_e32 v90, v90
	v_mul_f32_e32 v95, 0xbfb8aa3b, v97
	v_pk_mul_f32 v[92:93], v[92:93], v[100:101] op_sel_hi:[1,0]
	v_pk_mul_f32 v[88:89], v[88:89], v[100:101] op_sel_hi:[1,0]
	v_mul_f32_e32 v83, v91, v83
	v_mul_f32_e32 v91, 0xbfb8aa3b, v91
	v_exp_f32_e32 v95, v95
	v_add_f32_e32 v85, 1.0, v85
	v_add_f32_e32 v87, 1.0, v87
	v_mul_f32_e32 v88, v96, v88
	v_mul_f32_e32 v89, v97, v89
	v_mul_f32_e32 v96, 0xbfb8aa3b, v92
	v_mul_f32_e32 v97, 0xbfb8aa3b, v93
	v_exp_f32_e32 v91, v91
	v_add_f32_e32 v94, 1.0, v94
	v_add_f32_e32 v90, 1.0, v90
	v_rcp_f32_e32 v85, v85
	v_rcp_f32_e32 v87, v87
	v_exp_f32_e32 v96, v96
	v_exp_f32_e32 v97, v97
	v_rcp_f32_e32 v94, v94
	v_rcp_f32_e32 v90, v90
	v_add_f32_e32 v95, 1.0, v95
	v_add_f32_e32 v91, 1.0, v91
	v_rcp_f32_e32 v95, v95
	v_mul_f32_e32 v84, v84, v85
	v_mul_f32_e32 v85, v86, v87
	v_add_f32_e32 v96, 1.0, v96
	v_rcp_f32_e32 v91, v91
	v_mul_f32_e32 v86, v88, v94
	v_mul_f32_e32 v88, v82, v90
	v_cvt_pkrtz_f16_f32 v82, v84, v85
	v_add_f32_e32 v85, 1.0, v97
	v_rcp_f32_e32 v96, v96
	v_rcp_f32_e32 v85, v85
	v_mul_f32_e32 v87, v89, v95
	v_mul_f32_e32 v89, v83, v91
	v_cvt_pkrtz_f16_f32 v83, v86, v87
	v_mul_f32_e32 v86, v92, v102
	v_mul_f32_e32 v87, v93, v103
	v_mul_f32_e32 v86, v86, v96
	v_mul_f32_e32 v85, v87, v85
	v_cvt_pkrtz_f16_f32 v84, v88, v89
	v_cvt_pkrtz_f16_f32 v85, v86, v85
	global_store_dwordx4 v[98:99], v[82:85], off nt
	s_nop 1
	v_or_b32_e32 v82, 48, v146
	v_ashrrev_i32_e32 v83, 31, v82
	v_lshl_add_u64 v[84:85], v[82:83], 2, s[70:71]
	v_mov_b32_e32 v84, v194
	v_mad_i64_i32 v[82:83], s[8:9], v82, s91, v[114:115]
	v_lshl_add_u64 v[82:83], v[82:83], 0, v[116:117]
	v_pk_mul_f32 v[80:81], v[80:81], v[84:85] op_sel_hi:[1,0]
	v_pk_mul_f32 v[78:79], v[78:79], v[84:85] op_sel_hi:[1,0]
	v_pk_mul_f32 v[70:71], v[70:71], v[84:85] op_sel_hi:[1,0]
	v_pk_mul_f32 v[74:75], v[74:75], v[84:85] op_sel_hi:[1,0]
	v_pk_mul_f32 v[86:87], v[68:69], v[84:85] op_sel_hi:[1,0]
	v_pk_mul_f32 v[66:67], v[66:67], v[84:85] op_sel_hi:[1,0]
	v_mul_f32_e32 v68, v78, v70
	v_mul_f32_e32 v69, 0xbfb8aa3b, v78
	v_mul_f32_e32 v70, v79, v71
	v_mul_f32_e32 v71, 0xbfb8aa3b, v79
	v_mul_f32_e32 v78, 0xbfb8aa3b, v80
	v_mul_f32_e32 v79, 0xbfb8aa3b, v81
	v_pk_mul_f32 v[76:77], v[76:77], v[84:85] op_sel_hi:[1,0]
	v_pk_mul_f32 v[72:73], v[72:73], v[84:85] op_sel_hi:[1,0]
	v_mul_f32_e32 v66, v74, v66
	v_mul_f32_e32 v74, 0xbfb8aa3b, v74
	v_mul_f32_e32 v67, v75, v67
	v_mul_f32_e32 v75, 0xbfb8aa3b, v75
	v_exp_f32_e32 v69, v69
	v_exp_f32_e32 v71, v71
	v_exp_f32_e32 v78, v78
	v_exp_f32_e32 v79, v79
	v_mul_f32_e32 v72, v80, v72
	v_mul_f32_e32 v73, v81, v73
	v_mul_f32_e32 v80, 0xbfb8aa3b, v76
	v_mul_f32_e32 v81, 0xbfb8aa3b, v77
	v_exp_f32_e32 v74, v74
	v_exp_f32_e32 v75, v75
	v_exp_f32_e32 v80, v80
	v_exp_f32_e32 v81, v81
	v_add_f32_e32 v69, 1.0, v69
	v_add_f32_e32 v71, 1.0, v71
	v_add_f32_e32 v78, 1.0, v78
	v_add_f32_e32 v79, 1.0, v79
	v_add_f32_e32 v74, 1.0, v74
	v_add_f32_e32 v75, 1.0, v75
	v_rcp_f32_e32 v69, v69
	v_rcp_f32_e32 v71, v71
	v_rcp_f32_e32 v78, v78
	v_rcp_f32_e32 v79, v79
	v_add_f32_e32 v80, 1.0, v80
	v_add_f32_e32 v81, 1.0, v81
	v_rcp_f32_e32 v74, v74
	v_rcp_f32_e32 v75, v75
	v_rcp_f32_e32 v80, v80
	v_rcp_f32_e32 v81, v81
	v_mul_f32_e32 v68, v68, v69
	v_mul_f32_e32 v69, v70, v71
	v_mul_f32_e32 v70, v72, v78
	v_mul_f32_e32 v71, v73, v79
	v_mul_f32_e32 v72, v66, v74
	v_mul_f32_e32 v73, v67, v75
	v_cvt_pkrtz_f16_f32 v66, v68, v69
	v_cvt_pkrtz_f16_f32 v67, v70, v71
	v_mul_f32_e32 v69, v76, v86
	v_mul_f32_e32 v70, v77, v87
	v_mul_f32_e32 v69, v69, v80
	v_mul_f32_e32 v70, v70, v81
	v_cvt_pkrtz_f16_f32 v68, v72, v73
	v_cvt_pkrtz_f16_f32 v69, v69, v70
	global_store_dwordx4 v[82:83], v[66:69], off nt
	s_nop 1
	v_mov_b32_e32 v66, v195
	v_add_u32_e32 v67, 0x80, v146
	v_mad_i64_i32 v[68:69], s[8:9], v67, s91, v[114:115]
	v_lshl_add_u64 v[68:69], v[68:69], 0, v[116:117]
	v_pk_mul_f32 v[64:65], v[64:65], v[66:67] op_sel_hi:[1,0]
	v_pk_mul_f32 v[62:63], v[62:63], v[66:67] op_sel_hi:[1,0]
	v_pk_mul_f32 v[60:61], v[60:61], v[66:67] op_sel_hi:[1,0]
	v_pk_mul_f32 v[58:59], v[58:59], v[66:67] op_sel_hi:[1,0]
	v_pk_mul_f32 v[56:57], v[56:57], v[66:67] op_sel_hi:[1,0]
	v_pk_mul_f32 v[54:55], v[54:55], v[66:67] op_sel_hi:[1,0]
	v_pk_mul_f32 v[52:53], v[52:53], v[66:67] op_sel_hi:[1,0]
	v_pk_mul_f32 v[50:51], v[50:51], v[66:67] op_sel_hi:[1,0]
	v_mul_f32_e32 v54, v62, v54
	v_mul_f32_e32 v62, 0xbfb8aa3b, v62
	v_mul_f32_e32 v55, v63, v55
	v_mul_f32_e32 v63, 0xbfb8aa3b, v63
	v_mul_f32_e32 v56, v64, v56
	v_mul_f32_e32 v64, 0xbfb8aa3b, v64
	v_mul_f32_e32 v57, v65, v57
	v_mul_f32_e32 v65, 0xbfb8aa3b, v65
	v_mul_f32_e32 v50, v58, v50
	v_mul_f32_e32 v58, 0xbfb8aa3b, v58
	v_mul_f32_e32 v51, v59, v51
	v_mul_f32_e32 v59, 0xbfb8aa3b, v59
	v_mul_f32_e32 v52, v60, v52
	v_mul_f32_e32 v60, 0xbfb8aa3b, v60
	v_mul_f32_e32 v53, v61, v53
	v_mul_f32_e32 v61, 0xbfb8aa3b, v61
	v_exp_f32_e32 v62, v62
	v_exp_f32_e32 v63, v63
	v_exp_f32_e32 v64, v64
	v_exp_f32_e32 v65, v65
	v_exp_f32_e32 v58, v58
	v_exp_f32_e32 v59, v59
	v_exp_f32_e32 v60, v60
	v_exp_f32_e32 v61, v61
	v_add_f32_e32 v62, 1.0, v62
	v_add_f32_e32 v63, 1.0, v63
	v_add_f32_e32 v64, 1.0, v64
	v_add_f32_e32 v65, 1.0, v65
	v_add_f32_e32 v58, 1.0, v58
	v_add_f32_e32 v59, 1.0, v59
	v_add_f32_e32 v60, 1.0, v60
	v_add_f32_e32 v61, 1.0, v61
	v_rcp_f32_e32 v62, v62
	v_rcp_f32_e32 v63, v63
	v_rcp_f32_e32 v64, v64
	v_rcp_f32_e32 v65, v65
	v_rcp_f32_e32 v58, v58
	v_rcp_f32_e32 v59, v59
	v_rcp_f32_e32 v60, v60
	v_rcp_f32_e32 v61, v61
	v_mul_f32_e32 v54, v54, v62
	v_mul_f32_e32 v55, v55, v63
	v_mul_f32_e32 v56, v56, v64
	v_mul_f32_e32 v57, v57, v65
	v_mul_f32_e32 v58, v50, v58
	v_mul_f32_e32 v59, v51, v59
	v_mul_f32_e32 v60, v52, v60
	v_mul_f32_e32 v53, v53, v61
	v_cvt_pkrtz_f16_f32 v50, v54, v55
	v_cvt_pkrtz_f16_f32 v51, v56, v57
	v_cvt_pkrtz_f16_f32 v52, v58, v59
	v_cvt_pkrtz_f16_f32 v53, v60, v53
	global_store_dwordx4 v[68:69], v[50:53], off nt
	s_nop 1
	v_mov_b32_e32 v50, v196
	v_add_u32_e32 v51, 0x90, v146
	v_mad_i64_i32 v[52:53], s[8:9], v51, s91, v[114:115]
	v_lshl_add_u64 v[52:53], v[52:53], 0, v[116:117]
	v_pk_mul_f32 v[48:49], v[48:49], v[50:51] op_sel_hi:[1,0]
	v_pk_mul_f32 v[46:47], v[46:47], v[50:51] op_sel_hi:[1,0]
	v_pk_mul_f32 v[44:45], v[44:45], v[50:51] op_sel_hi:[1,0]
	v_pk_mul_f32 v[42:43], v[42:43], v[50:51] op_sel_hi:[1,0]
	v_pk_mul_f32 v[40:41], v[40:41], v[50:51] op_sel_hi:[1,0]
	v_pk_mul_f32 v[38:39], v[38:39], v[50:51] op_sel_hi:[1,0]
	v_pk_mul_f32 v[36:37], v[36:37], v[50:51] op_sel_hi:[1,0]
	v_pk_mul_f32 v[34:35], v[34:35], v[50:51] op_sel_hi:[1,0]
	v_mul_f32_e32 v38, v46, v38
	v_mul_f32_e32 v46, 0xbfb8aa3b, v46
	v_mul_f32_e32 v39, v47, v39
	v_mul_f32_e32 v47, 0xbfb8aa3b, v47
	v_mul_f32_e32 v40, v48, v40
	v_mul_f32_e32 v48, 0xbfb8aa3b, v48
	v_mul_f32_e32 v41, v49, v41
	v_mul_f32_e32 v49, 0xbfb8aa3b, v49
	v_mul_f32_e32 v34, v42, v34
	v_mul_f32_e32 v42, 0xbfb8aa3b, v42
	v_mul_f32_e32 v35, v43, v35
	v_mul_f32_e32 v43, 0xbfb8aa3b, v43
	v_mul_f32_e32 v36, v44, v36
	v_mul_f32_e32 v44, 0xbfb8aa3b, v44
	v_mul_f32_e32 v37, v45, v37
	v_mul_f32_e32 v45, 0xbfb8aa3b, v45
	v_exp_f32_e32 v46, v46
	v_exp_f32_e32 v47, v47
	v_exp_f32_e32 v48, v48
	v_exp_f32_e32 v49, v49
	v_exp_f32_e32 v42, v42
	v_exp_f32_e32 v43, v43
	v_exp_f32_e32 v44, v44
	v_exp_f32_e32 v45, v45
	v_add_f32_e32 v46, 1.0, v46
	v_add_f32_e32 v47, 1.0, v47
	v_add_f32_e32 v48, 1.0, v48
	v_add_f32_e32 v49, 1.0, v49
	v_add_f32_e32 v42, 1.0, v42
	v_add_f32_e32 v43, 1.0, v43
	v_add_f32_e32 v44, 1.0, v44
	v_add_f32_e32 v45, 1.0, v45
	v_rcp_f32_e32 v46, v46
	v_rcp_f32_e32 v47, v47
	v_rcp_f32_e32 v48, v48
	v_rcp_f32_e32 v49, v49
	v_rcp_f32_e32 v42, v42
	v_rcp_f32_e32 v43, v43
	v_rcp_f32_e32 v44, v44
	v_rcp_f32_e32 v45, v45
	v_mul_f32_e32 v38, v38, v46
	v_mul_f32_e32 v39, v39, v47
	v_mul_f32_e32 v40, v40, v48
	v_mul_f32_e32 v41, v41, v49
	v_mul_f32_e32 v42, v34, v42
	v_mul_f32_e32 v43, v35, v43
	v_mul_f32_e32 v44, v36, v44
	v_mul_f32_e32 v37, v37, v45
	v_cvt_pkrtz_f16_f32 v34, v38, v39
	v_cvt_pkrtz_f16_f32 v35, v40, v41
	v_cvt_pkrtz_f16_f32 v36, v42, v43
	v_cvt_pkrtz_f16_f32 v37, v44, v37
	global_store_dwordx4 v[52:53], v[34:37], off nt
	s_nop 1
	v_mov_b32_e32 v34, v197
	v_add_u32_e32 v35, 0xa0, v146
	v_mad_i64_i32 v[36:37], s[8:9], v35, s91, v[114:115]
	v_lshl_add_u64 v[36:37], v[36:37], 0, v[116:117]
	v_pk_mul_f32 v[32:33], v[32:33], v[34:35] op_sel_hi:[1,0]
	v_pk_mul_f32 v[30:31], v[30:31], v[34:35] op_sel_hi:[1,0]
	v_pk_mul_f32 v[28:29], v[28:29], v[34:35] op_sel_hi:[1,0]
	v_pk_mul_f32 v[26:27], v[26:27], v[34:35] op_sel_hi:[1,0]
	v_pk_mul_f32 v[24:25], v[24:25], v[34:35] op_sel_hi:[1,0]
	v_pk_mul_f32 v[22:23], v[22:23], v[34:35] op_sel_hi:[1,0]
	v_pk_mul_f32 v[20:21], v[20:21], v[34:35] op_sel_hi:[1,0]
	v_pk_mul_f32 v[18:19], v[18:19], v[34:35] op_sel_hi:[1,0]
	v_mul_f32_e32 v22, v30, v22
	v_mul_f32_e32 v30, 0xbfb8aa3b, v30
	v_mul_f32_e32 v23, v31, v23
	v_mul_f32_e32 v31, 0xbfb8aa3b, v31
	v_mul_f32_e32 v24, v32, v24
	v_mul_f32_e32 v32, 0xbfb8aa3b, v32
	v_mul_f32_e32 v25, v33, v25
	v_mul_f32_e32 v33, 0xbfb8aa3b, v33
	v_mul_f32_e32 v18, v26, v18
	v_mul_f32_e32 v26, 0xbfb8aa3b, v26
	v_mul_f32_e32 v19, v27, v19
	v_mul_f32_e32 v27, 0xbfb8aa3b, v27
	v_mul_f32_e32 v20, v28, v20
	v_mul_f32_e32 v28, 0xbfb8aa3b, v28
	v_mul_f32_e32 v21, v29, v21
	v_mul_f32_e32 v29, 0xbfb8aa3b, v29
	v_exp_f32_e32 v30, v30
	v_exp_f32_e32 v31, v31
	v_exp_f32_e32 v32, v32
	v_exp_f32_e32 v33, v33
	v_exp_f32_e32 v26, v26
	v_exp_f32_e32 v27, v27
	v_exp_f32_e32 v28, v28
	v_exp_f32_e32 v29, v29
	v_add_f32_e32 v30, 1.0, v30
	v_add_f32_e32 v31, 1.0, v31
	v_add_f32_e32 v32, 1.0, v32
	v_add_f32_e32 v33, 1.0, v33
	v_add_f32_e32 v26, 1.0, v26
	v_add_f32_e32 v27, 1.0, v27
	v_add_f32_e32 v28, 1.0, v28
	v_add_f32_e32 v29, 1.0, v29
	v_rcp_f32_e32 v30, v30
	v_rcp_f32_e32 v31, v31
	v_rcp_f32_e32 v32, v32
	v_rcp_f32_e32 v33, v33
	v_rcp_f32_e32 v26, v26
	v_rcp_f32_e32 v27, v27
	v_rcp_f32_e32 v28, v28
	v_rcp_f32_e32 v29, v29
	v_mul_f32_e32 v22, v22, v30
	v_mul_f32_e32 v23, v23, v31
	v_mul_f32_e32 v24, v24, v32
	v_mul_f32_e32 v25, v25, v33
	v_mul_f32_e32 v26, v18, v26
	v_mul_f32_e32 v27, v19, v27
	v_mul_f32_e32 v28, v20, v28
	v_mul_f32_e32 v21, v21, v29
	v_cvt_pkrtz_f16_f32 v18, v22, v23
	v_cvt_pkrtz_f16_f32 v19, v24, v25
	v_cvt_pkrtz_f16_f32 v20, v26, v27
	v_cvt_pkrtz_f16_f32 v21, v28, v21
	global_store_dwordx4 v[36:37], v[18:21], off nt
	s_nop 1
	v_mov_b32_e32 v18, v198
	v_add_u32_e32 v19, 0xb0, v146
	v_mad_i64_i32 v[20:21], s[8:9], v19, s91, v[114:115]
	v_lshl_add_u64 v[20:21], v[20:21], 0, v[116:117]
	v_pk_mul_f32 v[16:17], v[16:17], v[18:19] op_sel_hi:[1,0]
	v_pk_mul_f32 v[14:15], v[14:15], v[18:19] op_sel_hi:[1,0]
	v_pk_mul_f32 v[12:13], v[12:13], v[18:19] op_sel_hi:[1,0]
	v_pk_mul_f32 v[10:11], v[10:11], v[18:19] op_sel_hi:[1,0]
	v_pk_mul_f32 v[8:9], v[8:9], v[18:19] op_sel_hi:[1,0]
	v_pk_mul_f32 v[6:7], v[6:7], v[18:19] op_sel_hi:[1,0]
	v_pk_mul_f32 v[4:5], v[4:5], v[18:19] op_sel_hi:[1,0]
	v_pk_mul_f32 v[2:3], v[2:3], v[18:19] op_sel_hi:[1,0]
	v_mul_f32_e32 v6, v14, v6
	v_mul_f32_e32 v14, 0xbfb8aa3b, v14
	v_mul_f32_e32 v7, v15, v7
	v_mul_f32_e32 v15, 0xbfb8aa3b, v15
	v_mul_f32_e32 v8, v16, v8
	v_mul_f32_e32 v16, 0xbfb8aa3b, v16
	v_mul_f32_e32 v9, v17, v9
	v_mul_f32_e32 v17, 0xbfb8aa3b, v17
	v_mul_f32_e32 v2, v10, v2
	v_mul_f32_e32 v10, 0xbfb8aa3b, v10
	v_mul_f32_e32 v3, v11, v3
	v_mul_f32_e32 v11, 0xbfb8aa3b, v11
	v_mul_f32_e32 v4, v12, v4
	v_mul_f32_e32 v12, 0xbfb8aa3b, v12
	v_mul_f32_e32 v5, v13, v5
	v_mul_f32_e32 v13, 0xbfb8aa3b, v13
	v_exp_f32_e32 v14, v14
	v_exp_f32_e32 v15, v15
	v_exp_f32_e32 v16, v16
	v_exp_f32_e32 v17, v17
	v_exp_f32_e32 v10, v10
	v_exp_f32_e32 v11, v11
	v_exp_f32_e32 v12, v12
	v_exp_f32_e32 v13, v13
	v_add_f32_e32 v14, 1.0, v14
	v_add_f32_e32 v15, 1.0, v15
	v_add_f32_e32 v16, 1.0, v16
	v_add_f32_e32 v17, 1.0, v17
	v_add_f32_e32 v10, 1.0, v10
	v_add_f32_e32 v11, 1.0, v11
	v_add_f32_e32 v12, 1.0, v12
	v_add_f32_e32 v13, 1.0, v13
	v_rcp_f32_e32 v14, v14
	v_rcp_f32_e32 v15, v15
	v_rcp_f32_e32 v16, v16
	v_rcp_f32_e32 v17, v17
	v_rcp_f32_e32 v10, v10
	v_rcp_f32_e32 v11, v11
	v_rcp_f32_e32 v12, v12
	v_rcp_f32_e32 v13, v13
	v_mul_f32_e32 v6, v6, v14
	v_mul_f32_e32 v7, v7, v15
	v_mul_f32_e32 v8, v8, v16
	v_mul_f32_e32 v9, v9, v17
	v_mul_f32_e32 v10, v2, v10
	v_mul_f32_e32 v11, v3, v11
	v_mul_f32_e32 v12, v4, v12
	v_mul_f32_e32 v5, v5, v13
	v_cvt_pkrtz_f16_f32 v2, v6, v7
	v_cvt_pkrtz_f16_f32 v3, v8, v9
	v_cvt_pkrtz_f16_f32 v4, v10, v11
	v_cvt_pkrtz_f16_f32 v5, v12, v5
	global_store_dwordx4 v[20:21], v[2:5], off nt
	s_cbranch_vccnz .LBB0_209
	s_andn2_b64 vcc, exec, s[0:1]
	s_cbranch_vccnz .LBB0_208
	s_barrier
	s_branch .LBB0_208

.LBB0_1018:
	v_lshl_or_b32 v172, s59, 7, v155
	v_ashrrev_i32_e32 v173, 31, v172
	v_lshlrev_b64 v[146:147], 2, v[172:173]
	v_lshl_add_u64 v[152:153], s[6:7], 0, v[146:147]
	v_lshl_add_u64 v[146:147], s[16:17], 0, v[146:147]
	global_load_dwordx4 v[148:151], v[152:153], off
	global_load_dwordx4 v[160:163], v[152:153], off offset:16
	global_load_dwordx4 v[164:167], v[146:147], off
	global_load_dwordx4 v[168:171], v[146:147], off offset:16
	v_lshl_add_u32 v146, s40, 8, v1
	v_ashrrev_i32_e32 v147, 31, v146
	v_lshl_add_u64 v[152:153], v[146:147], 2, s[70:71]
	global_load_dword v174, v[152:153], off
	global_load_dword v192, v[152:153], off offset:64
	global_load_dword v193, v[152:153], off offset:128
	global_load_dword v194, v[152:153], off offset:192
	global_load_dword v195, v[152:153], off offset:512
	global_load_dword v196, v[152:153], off offset:576
	global_load_dword v197, v[152:153], off offset:640
	global_load_dword v198, v[152:153], off offset:704
	v_cvt_f32_i32_e32 v177, v127
	v_cvt_f32_i32_e32 v176, v126
	v_cvt_f32_i32_e32 v185, v119
	v_cvt_f32_i32_e32 v184, v118
	v_cvt_f32_i32_e32 v179, v129
	v_cvt_f32_i32_e32 v178, v128
	v_cvt_f32_i32_e32 v187, v121
	v_cvt_f32_i32_e32 v186, v120
	v_cvt_f32_i32_e32 v189, v115
	v_cvt_f32_i32_e32 v188, v114
	v_mov_b64_e32 v[114:115], s[38:39]
	v_cvt_f32_i32_e32 v191, v117
	v_cvt_f32_i32_e32 v190, v116
	v_mad_i64_i32 v[118:119], s[8:9], v146, s58, v[114:115]
	v_lshlrev_b64 v[116:117], 1, v[172:173]
	v_cvt_f32_i32_e32 v181, v123
	v_cvt_f32_i32_e32 v180, v122
	v_lshl_add_u64 v[172:173], v[118:119], 0, v[116:117]
	v_cvt_f32_i32_e32 v183, v125
	v_cvt_f32_i32_e32 v182, v124
	v_cvt_f32_i32_e32 v111, v111
	v_cvt_f32_i32_e32 v110, v110
	v_cvt_f32_i32_e32 v103, v103
	v_cvt_f32_i32_e32 v102, v102
	v_cvt_f32_i32_e32 v113, v113
	v_cvt_f32_i32_e32 v112, v112
	v_cvt_f32_i32_e32 v107, v107
	v_cvt_f32_i32_e32 v106, v106
	v_cvt_f32_i32_e32 v99, v99
	v_cvt_f32_i32_e32 v98, v98
	v_cvt_f32_i32_e32 v101, v101
	v_cvt_f32_i32_e32 v100, v100
	v_cvt_f32_i32_e32 v109, v109
	v_cvt_f32_i32_e32 v108, v108
	v_cvt_f32_i32_e32 v105, v105
	v_cvt_f32_i32_e32 v104, v104
	v_cvt_f32_i32_e32 v95, v95
	v_cvt_f32_i32_e32 v94, v94
	v_cvt_f32_i32_e32 v87, v87
	v_cvt_f32_i32_e32 v86, v86
	v_cvt_f32_i32_e32 v97, v97
	v_cvt_f32_i32_e32 v96, v96
	v_cvt_f32_i32_e32 v91, v91
	v_cvt_f32_i32_e32 v90, v90
	v_cvt_f32_i32_e32 v83, v83
	v_cvt_f32_i32_e32 v82, v82
	v_cvt_f32_i32_e32 v85, v85
	v_cvt_f32_i32_e32 v84, v84
	v_cvt_f32_i32_e32 v93, v93
	v_cvt_f32_i32_e32 v92, v92
	v_cvt_f32_i32_e32 v89, v89
	v_cvt_f32_i32_e32 v88, v88
	v_cvt_f32_i32_e32 v79, v79
	v_cvt_f32_i32_e32 v78, v78
	v_cvt_f32_i32_e32 v81, v81
	v_cvt_f32_i32_e32 v80, v80
	v_cvt_f32_i32_e32 v71, v71
	v_cvt_f32_i32_e32 v70, v70
	v_cvt_f32_i32_e32 v75, v75
	v_cvt_f32_i32_e32 v74, v74
	v_cvt_f32_i32_e32 v67, v67
	v_cvt_f32_i32_e32 v66, v66
	v_cvt_f32_i32_e32 v69, v69
	v_cvt_f32_i32_e32 v68, v68
	v_cvt_f32_i32_e32 v77, v77
	v_cvt_f32_i32_e32 v76, v76
	v_cvt_f32_i32_e32 v73, v73
	v_cvt_f32_i32_e32 v72, v72
	v_cvt_f32_i32_e32 v63, v63
	v_cvt_f32_i32_e32 v62, v62
	v_cvt_f32_i32_e32 v65, v65
	v_cvt_f32_i32_e32 v64, v64
	s_waitcnt vmcnt(0)
	v_pk_mul_f32 v[120:121], v[148:149], s[18:19] op_sel_hi:[1,0]
	v_pk_mul_f32 v[128:129], v[164:165], s[18:19] op_sel_hi:[1,0]
	v_pk_mul_f32 v[118:119], v[150:151], s[18:19] op_sel_hi:[1,0]
	v_pk_mul_f32 v[122:123], v[162:163], s[18:19] op_sel_hi:[1,0]
	v_pk_mul_f32 v[126:127], v[166:167], s[18:19] op_sel_hi:[1,0]
	v_pk_mul_f32 v[148:149], v[170:171], s[18:19] op_sel_hi:[1,0]
	v_pk_mul_f32 v[162:163], v[120:121], v[176:177]
	v_pk_mul_f32 v[170:171], v[128:129], v[184:185]
	v_pk_mul_f32 v[124:125], v[160:161], s[18:19] op_sel_hi:[1,0]
	v_pk_mul_f32 v[150:151], v[168:169], s[18:19] op_sel_hi:[1,0]
	v_pk_mul_f32 v[160:161], v[118:119], v[178:179]
	v_pk_mul_f32 v[168:169], v[126:127], v[186:187]
	v_pk_mul_f32 v[162:163], v[162:163], v[174:175] op_sel_hi:[1,0]
	v_pk_mul_f32 v[170:171], v[170:171], v[174:175] op_sel_hi:[1,0]
	v_pk_mul_f32 v[160:161], v[160:161], v[174:175] op_sel_hi:[1,0]
	v_pk_mul_f32 v[168:169], v[168:169], v[174:175] op_sel_hi:[1,0]
	v_mul_f32_e32 v147, v162, v170
	v_mul_f32_e32 v159, 0xbfb8aa3b, v162
	v_mul_f32_e32 v162, v163, v171
	v_mul_f32_e32 v163, 0xbfb8aa3b, v163
	v_mul_f32_e32 v168, v160, v168
	v_mul_f32_e32 v160, 0xbfb8aa3b, v160
	v_exp_f32_e32 v159, v159
	v_exp_f32_e32 v163, v163
	v_exp_f32_e32 v160, v160
	v_pk_mul_f32 v[164:165], v[122:123], v[182:183]
	v_pk_mul_f32 v[166:167], v[124:125], v[180:181]
	v_pk_mul_f32 v[176:177], v[148:149], v[190:191]
	v_pk_mul_f32 v[178:179], v[150:151], v[188:189]
	v_add_f32_e32 v159, 1.0, v159
	v_add_f32_e32 v163, 1.0, v163
	v_pk_mul_f32 v[164:165], v[164:165], v[174:175] op_sel_hi:[1,0]
	v_pk_mul_f32 v[166:167], v[166:167], v[174:175] op_sel_hi:[1,0]
	v_pk_mul_f32 v[176:177], v[176:177], v[174:175] op_sel_hi:[1,0]
	v_pk_mul_f32 v[174:175], v[178:179], v[174:175] op_sel_hi:[1,0]
	v_add_f32_e32 v160, 1.0, v160
	v_rcp_f32_e32 v159, v159
	v_rcp_f32_e32 v163, v163
	v_mul_f32_e32 v169, v161, v169
	v_mul_f32_e32 v161, 0xbfb8aa3b, v161
	v_mul_f32_e32 v170, v166, v174
	v_mul_f32_e32 v166, 0xbfb8aa3b, v166
	v_mul_f32_e32 v171, v167, v175
	v_mul_f32_e32 v167, 0xbfb8aa3b, v167
	v_rcp_f32_e32 v160, v160
	v_exp_f32_e32 v161, v161
	v_exp_f32_e32 v166, v166
	v_exp_f32_e32 v167, v167
	v_mul_f32_e32 v174, 0xbfb8aa3b, v164
	v_mul_f32_e32 v175, 0xbfb8aa3b, v165
	v_exp_f32_e32 v174, v174
	v_mul_f32_e32 v147, v147, v159
	v_mul_f32_e32 v159, v162, v163
	v_mul_f32_e32 v162, v168, v160
	v_cvt_pkrtz_f16_f32 v160, v147, v159
	v_exp_f32_e32 v147, v175
	v_add_f32_e32 v161, 1.0, v161
	v_add_f32_e32 v166, 1.0, v166
	v_add_f32_e32 v167, 1.0, v167
	v_rcp_f32_e32 v161, v161
	v_rcp_f32_e32 v166, v166
	v_rcp_f32_e32 v167, v167
	v_add_f32_e32 v159, 1.0, v174
	v_rcp_f32_e32 v159, v159
	v_add_f32_e32 v147, 1.0, v147
	v_rcp_f32_e32 v147, v147
	v_mul_f32_e32 v161, v169, v161
	v_mul_f32_e32 v163, v170, v166
	v_mul_f32_e32 v166, v171, v167
	v_cvt_pkrtz_f16_f32 v161, v162, v161
	v_cvt_pkrtz_f16_f32 v162, v163, v166
	v_mul_f32_e32 v163, v164, v176
	v_mul_f32_e32 v159, v163, v159
	v_mul_f32_e32 v163, v165, v177
	v_mul_f32_e32 v147, v163, v147
	v_cvt_pkrtz_f16_f32 v163, v159, v147
	global_store_dwordx4 v[172:173], v[160:163], off nt
	v_pk_mul_f32 v[110:111], v[120:121], v[110:111]
	v_pk_mul_f32 v[102:103], v[128:129], v[102:103]
	v_or_b32_e32 v160, 16, v146
	v_ashrrev_i32_e32 v161, 31, v160
	v_lshl_add_u64 v[162:163], v[160:161], 2, s[70:71]
	v_mov_b32_e32 v162, v192
	v_pk_mul_f32 v[112:113], v[118:119], v[112:113]
	v_pk_mul_f32 v[106:107], v[124:125], v[106:107]
	v_pk_mul_f32 v[100:101], v[148:149], v[100:101]
	v_pk_mul_f32 v[98:99], v[150:151], v[98:99]
	v_pk_mul_f32 v[108:109], v[122:123], v[108:109]
	v_pk_mul_f32 v[104:105], v[126:127], v[104:105]
	v_mad_i64_i32 v[160:161], s[8:9], v160, s58, v[114:115]
	v_lshl_add_u64 v[160:161], v[160:161], 0, v[116:117]
	v_pk_mul_f32 v[94:95], v[120:121], v[94:95]
	v_pk_mul_f32 v[86:87], v[128:129], v[86:87]
	v_pk_mul_f32 v[96:97], v[118:119], v[96:97]
	v_pk_mul_f32 v[90:91], v[124:125], v[90:91]
	v_pk_mul_f32 v[84:85], v[148:149], v[84:85]
	v_pk_mul_f32 v[82:83], v[150:151], v[82:83]
	v_pk_mul_f32 v[92:93], v[122:123], v[92:93]
	v_pk_mul_f32 v[88:89], v[126:127], v[88:89]
	v_pk_mul_f32 v[80:81], v[118:119], v[80:81]
	v_pk_mul_f32 v[78:79], v[120:121], v[78:79]
	v_pk_mul_f32 v[70:71], v[128:129], v[70:71]
	v_pk_mul_f32 v[74:75], v[124:125], v[74:75]
	v_pk_mul_f32 v[68:69], v[148:149], v[68:69]
	v_pk_mul_f32 v[66:67], v[150:151], v[66:67]
	v_pk_mul_f32 v[76:77], v[122:123], v[76:77]
	v_pk_mul_f32 v[72:73], v[126:127], v[72:73]
	v_cvt_f32_i32_e32 v59, v59
	v_cvt_f32_i32_e32 v58, v58
	v_cvt_f32_i32_e32 v61, v61
	v_cvt_f32_i32_e32 v60, v60
	v_cvt_f32_i32_e32 v55, v55
	v_cvt_f32_i32_e32 v54, v54
	v_cvt_f32_i32_e32 v57, v57
	v_cvt_f32_i32_e32 v56, v56
	v_cvt_f32_i32_e32 v51, v51
	v_cvt_f32_i32_e32 v50, v50
	v_cvt_f32_i32_e32 v53, v53
	v_cvt_f32_i32_e32 v52, v52
	v_pk_mul_f32 v[64:65], v[118:119], v[64:65]
	v_pk_mul_f32 v[62:63], v[120:121], v[62:63]
	v_pk_mul_f32 v[60:61], v[122:123], v[60:61]
	v_pk_mul_f32 v[58:59], v[124:125], v[58:59]
	v_pk_mul_f32 v[56:57], v[126:127], v[56:57]
	v_pk_mul_f32 v[54:55], v[128:129], v[54:55]
	v_pk_mul_f32 v[52:53], v[148:149], v[52:53]
	v_pk_mul_f32 v[50:51], v[150:151], v[50:51]
	v_cvt_f32_i32_e32 v47, v47
	v_cvt_f32_i32_e32 v46, v46
	v_cvt_f32_i32_e32 v49, v49
	v_cvt_f32_i32_e32 v48, v48
	v_cvt_f32_i32_e32 v43, v43
	v_cvt_f32_i32_e32 v42, v42
	v_cvt_f32_i32_e32 v45, v45
	v_cvt_f32_i32_e32 v44, v44
	v_cvt_f32_i32_e32 v39, v39
	v_cvt_f32_i32_e32 v38, v38
	v_cvt_f32_i32_e32 v41, v41
	v_cvt_f32_i32_e32 v40, v40
	v_cvt_f32_i32_e32 v35, v35
	v_cvt_f32_i32_e32 v34, v34
	v_cvt_f32_i32_e32 v37, v37
	v_cvt_f32_i32_e32 v36, v36
	v_pk_mul_f32 v[48:49], v[118:119], v[48:49]
	v_pk_mul_f32 v[46:47], v[120:121], v[46:47]
	v_pk_mul_f32 v[44:45], v[122:123], v[44:45]
	v_pk_mul_f32 v[42:43], v[124:125], v[42:43]
	v_pk_mul_f32 v[40:41], v[126:127], v[40:41]
	v_pk_mul_f32 v[38:39], v[128:129], v[38:39]
	v_pk_mul_f32 v[36:37], v[148:149], v[36:37]
	v_pk_mul_f32 v[34:35], v[150:151], v[34:35]
	v_cvt_f32_i32_e32 v31, v31
	v_cvt_f32_i32_e32 v30, v30
	v_cvt_f32_i32_e32 v33, v33
	v_cvt_f32_i32_e32 v32, v32
	v_cvt_f32_i32_e32 v27, v27
	v_cvt_f32_i32_e32 v26, v26
	v_cvt_f32_i32_e32 v29, v29
	v_cvt_f32_i32_e32 v28, v28
	v_cvt_f32_i32_e32 v23, v23
	v_cvt_f32_i32_e32 v22, v22
	v_pk_mul_f32 v[110:111], v[110:111], v[162:163] op_sel_hi:[1,0]
	v_pk_mul_f32 v[102:103], v[102:103], v[162:163] op_sel_hi:[1,0]
	v_pk_mul_f32 v[112:113], v[112:113], v[162:163] op_sel_hi:[1,0]
	v_pk_mul_f32 v[106:107], v[106:107], v[162:163] op_sel_hi:[1,0]
	v_pk_mul_f32 v[164:165], v[100:101], v[162:163] op_sel_hi:[1,0]
	v_pk_mul_f32 v[98:99], v[98:99], v[162:163] op_sel_hi:[1,0]
	v_mul_f32_e32 v100, v110, v102
	v_mul_f32_e32 v101, 0xbfb8aa3b, v110
	v_mul_f32_e32 v102, v111, v103
	v_mul_f32_e32 v103, 0xbfb8aa3b, v111
	v_mul_f32_e32 v110, 0xbfb8aa3b, v112
	v_mul_f32_e32 v111, 0xbfb8aa3b, v113
	v_mul_f32_e32 v98, v106, v98
	v_mul_f32_e32 v106, 0xbfb8aa3b, v106
	v_exp_f32_e32 v101, v101
	v_exp_f32_e32 v103, v103
	v_mul_f32_e32 v99, v107, v99
	v_mul_f32_e32 v107, 0xbfb8aa3b, v107
	v_exp_f32_e32 v110, v110
	v_exp_f32_e32 v111, v111
	v_exp_f32_e32 v106, v106
	v_exp_f32_e32 v107, v107
	v_pk_mul_f32 v[108:109], v[108:109], v[162:163] op_sel_hi:[1,0]
	v_pk_mul_f32 v[104:105], v[104:105], v[162:163] op_sel_hi:[1,0]
	v_add_f32_e32 v101, 1.0, v101
	v_add_f32_e32 v103, 1.0, v103
	v_mul_f32_e32 v104, v112, v104
	v_mul_f32_e32 v112, 0xbfb8aa3b, v108
	v_add_f32_e32 v110, 1.0, v110
	v_add_f32_e32 v111, 1.0, v111
	v_add_f32_e32 v106, 1.0, v106
	v_rcp_f32_e32 v101, v101
	v_rcp_f32_e32 v103, v103
	v_mul_f32_e32 v105, v113, v105
	v_mul_f32_e32 v113, 0xbfb8aa3b, v109
	v_exp_f32_e32 v112, v112
	v_add_f32_e32 v107, 1.0, v107
	v_rcp_f32_e32 v110, v110
	v_rcp_f32_e32 v111, v111
	v_rcp_f32_e32 v106, v106
	v_exp_f32_e32 v113, v113
	v_rcp_f32_e32 v107, v107
	v_mul_f32_e32 v100, v100, v101
	v_mul_f32_e32 v101, v102, v103
	v_mul_f32_e32 v102, v104, v110
	v_mul_f32_e32 v103, v105, v111
	v_mul_f32_e32 v104, v98, v106
	v_cvt_pkrtz_f16_f32 v98, v100, v101
	v_add_f32_e32 v101, 1.0, v112
	v_mul_f32_e32 v105, v99, v107
	v_cvt_pkrtz_f16_f32 v99, v102, v103
	v_rcp_f32_e32 v101, v101
	v_add_f32_e32 v102, 1.0, v113
	v_rcp_f32_e32 v102, v102
	v_mul_f32_e32 v103, v108, v164
	v_mul_f32_e32 v101, v103, v101
	v_mul_f32_e32 v103, v109, v165
	v_mul_f32_e32 v102, v103, v102
	v_cvt_pkrtz_f16_f32 v100, v104, v105
	v_cvt_pkrtz_f16_f32 v101, v101, v102
	global_store_dwordx4 v[160:161], v[98:101], off nt
	v_cvt_f32_i32_e32 v25, v25
	v_cvt_f32_i32_e32 v24, v24
	v_or_b32_e32 v98, 32, v146
	v_ashrrev_i32_e32 v99, 31, v98
	v_lshl_add_u64 v[100:101], v[98:99], 2, s[70:71]
	v_mov_b32_e32 v100, v193
	v_mad_i64_i32 v[98:99], s[8:9], v98, s58, v[114:115]
	v_lshl_add_u64 v[98:99], v[98:99], 0, v[116:117]
	v_cvt_f32_i32_e32 v19, v19
	v_cvt_f32_i32_e32 v18, v18
	v_cvt_f32_i32_e32 v21, v21
	v_cvt_f32_i32_e32 v20, v20
	v_pk_mul_f32 v[32:33], v[118:119], v[32:33]
	v_pk_mul_f32 v[30:31], v[120:121], v[30:31]
	v_pk_mul_f32 v[28:29], v[122:123], v[28:29]
	v_pk_mul_f32 v[26:27], v[124:125], v[26:27]
	v_pk_mul_f32 v[24:25], v[126:127], v[24:25]
	v_pk_mul_f32 v[22:23], v[128:129], v[22:23]
	v_pk_mul_f32 v[20:21], v[148:149], v[20:21]
	v_pk_mul_f32 v[18:19], v[150:151], v[18:19]
	v_cvt_f32_i32_e32 v15, v15
	v_cvt_f32_i32_e32 v14, v14
	v_cvt_f32_i32_e32 v17, v17
	v_cvt_f32_i32_e32 v16, v16
	v_cvt_f32_i32_e32 v11, v11
	v_cvt_f32_i32_e32 v10, v10
	v_cvt_f32_i32_e32 v13, v13
	v_cvt_f32_i32_e32 v12, v12
	v_cvt_f32_i32_e32 v7, v7
	v_cvt_f32_i32_e32 v6, v6
	v_cvt_f32_i32_e32 v9, v9
	v_cvt_f32_i32_e32 v8, v8
	v_cvt_f32_i32_e32 v3, v3
	v_cvt_f32_i32_e32 v2, v2
	v_cvt_f32_i32_e32 v5, v5
	v_cvt_f32_i32_e32 v4, v4
	v_pk_mul_f32 v[16:17], v[118:119], v[16:17]
	v_pk_mul_f32 v[14:15], v[120:121], v[14:15]
	v_pk_mul_f32 v[12:13], v[122:123], v[12:13]
	v_pk_mul_f32 v[10:11], v[124:125], v[10:11]
	v_pk_mul_f32 v[8:9], v[126:127], v[8:9]
	v_pk_mul_f32 v[6:7], v[128:129], v[6:7]
	v_pk_mul_f32 v[4:5], v[148:149], v[4:5]
	v_pk_mul_f32 v[2:3], v[150:151], v[2:3]
	s_andn2_b64 vcc, exec, s[2:3]
	s_mov_b64 s[2:3], -1
	v_pk_mul_f32 v[94:95], v[94:95], v[100:101] op_sel_hi:[1,0]
	v_pk_mul_f32 v[86:87], v[86:87], v[100:101] op_sel_hi:[1,0]
	v_pk_mul_f32 v[96:97], v[96:97], v[100:101] op_sel_hi:[1,0]
	v_pk_mul_f32 v[90:91], v[90:91], v[100:101] op_sel_hi:[1,0]
	v_pk_mul_f32 v[102:103], v[84:85], v[100:101] op_sel_hi:[1,0]
	v_pk_mul_f32 v[82:83], v[82:83], v[100:101] op_sel_hi:[1,0]
	v_mul_f32_e32 v84, v94, v86
	v_mul_f32_e32 v85, 0xbfb8aa3b, v94
	v_mul_f32_e32 v86, v95, v87
	v_mul_f32_e32 v87, 0xbfb8aa3b, v95
	v_mul_f32_e32 v94, 0xbfb8aa3b, v96
	v_mul_f32_e32 v82, v90, v82
	v_mul_f32_e32 v90, 0xbfb8aa3b, v90
	v_exp_f32_e32 v85, v85
	v_exp_f32_e32 v87, v87
	v_exp_f32_e32 v94, v94
	v_exp_f32_e32 v90, v90
	v_mul_f32_e32 v95, 0xbfb8aa3b, v97
	v_pk_mul_f32 v[92:93], v[92:93], v[100:101] op_sel_hi:[1,0]
	v_pk_mul_f32 v[88:89], v[88:89], v[100:101] op_sel_hi:[1,0]
	v_mul_f32_e32 v83, v91, v83
	v_mul_f32_e32 v91, 0xbfb8aa3b, v91
	v_exp_f32_e32 v95, v95
	v_add_f32_e32 v85, 1.0, v85
	v_add_f32_e32 v87, 1.0, v87
	v_mul_f32_e32 v88, v96, v88
	v_mul_f32_e32 v89, v97, v89
	v_mul_f32_e32 v96, 0xbfb8aa3b, v92
	v_mul_f32_e32 v97, 0xbfb8aa3b, v93
	v_exp_f32_e32 v91, v91
	v_add_f32_e32 v94, 1.0, v94
	v_add_f32_e32 v90, 1.0, v90
	v_rcp_f32_e32 v85, v85
	v_rcp_f32_e32 v87, v87
	v_exp_f32_e32 v96, v96
	v_exp_f32_e32 v97, v97
	v_rcp_f32_e32 v94, v94
	v_rcp_f32_e32 v90, v90
	v_add_f32_e32 v95, 1.0, v95
	v_add_f32_e32 v91, 1.0, v91
	v_rcp_f32_e32 v95, v95
	v_mul_f32_e32 v84, v84, v85
	v_mul_f32_e32 v85, v86, v87
	v_add_f32_e32 v96, 1.0, v96
	v_rcp_f32_e32 v91, v91
	v_mul_f32_e32 v86, v88, v94
	v_mul_f32_e32 v88, v82, v90
	v_cvt_pkrtz_f16_f32 v82, v84, v85
	v_add_f32_e32 v85, 1.0, v97
	v_rcp_f32_e32 v96, v96
	v_rcp_f32_e32 v85, v85
	v_mul_f32_e32 v87, v89, v95
	v_mul_f32_e32 v89, v83, v91
	v_cvt_pkrtz_f16_f32 v83, v86, v87
	v_mul_f32_e32 v86, v92, v102
	v_mul_f32_e32 v87, v93, v103
	v_mul_f32_e32 v86, v86, v96
	v_mul_f32_e32 v85, v87, v85
	v_cvt_pkrtz_f16_f32 v84, v88, v89
	v_cvt_pkrtz_f16_f32 v85, v86, v85
	global_store_dwordx4 v[98:99], v[82:85], off nt
	s_nop 1
	v_or_b32_e32 v82, 48, v146
	v_ashrrev_i32_e32 v83, 31, v82
	v_lshl_add_u64 v[84:85], v[82:83], 2, s[70:71]
	v_mov_b32_e32 v84, v194
	v_mad_i64_i32 v[82:83], s[8:9], v82, s58, v[114:115]
	v_lshl_add_u64 v[82:83], v[82:83], 0, v[116:117]
	v_pk_mul_f32 v[80:81], v[80:81], v[84:85] op_sel_hi:[1,0]
	v_pk_mul_f32 v[78:79], v[78:79], v[84:85] op_sel_hi:[1,0]
	v_pk_mul_f32 v[70:71], v[70:71], v[84:85] op_sel_hi:[1,0]
	v_pk_mul_f32 v[74:75], v[74:75], v[84:85] op_sel_hi:[1,0]
	v_pk_mul_f32 v[86:87], v[68:69], v[84:85] op_sel_hi:[1,0]
	v_pk_mul_f32 v[66:67], v[66:67], v[84:85] op_sel_hi:[1,0]
	v_mul_f32_e32 v68, v78, v70
	v_mul_f32_e32 v69, 0xbfb8aa3b, v78
	v_mul_f32_e32 v70, v79, v71
	v_mul_f32_e32 v71, 0xbfb8aa3b, v79
	v_mul_f32_e32 v78, 0xbfb8aa3b, v80
	v_mul_f32_e32 v79, 0xbfb8aa3b, v81
	v_pk_mul_f32 v[76:77], v[76:77], v[84:85] op_sel_hi:[1,0]
	v_pk_mul_f32 v[72:73], v[72:73], v[84:85] op_sel_hi:[1,0]
	v_mul_f32_e32 v66, v74, v66
	v_mul_f32_e32 v74, 0xbfb8aa3b, v74
	v_mul_f32_e32 v67, v75, v67
	v_mul_f32_e32 v75, 0xbfb8aa3b, v75
	v_exp_f32_e32 v69, v69
	v_exp_f32_e32 v71, v71
	v_exp_f32_e32 v78, v78
	v_exp_f32_e32 v79, v79
	v_mul_f32_e32 v72, v80, v72
	v_mul_f32_e32 v73, v81, v73
	v_mul_f32_e32 v80, 0xbfb8aa3b, v76
	v_mul_f32_e32 v81, 0xbfb8aa3b, v77
	v_exp_f32_e32 v74, v74
	v_exp_f32_e32 v75, v75
	v_exp_f32_e32 v80, v80
	v_exp_f32_e32 v81, v81
	v_add_f32_e32 v69, 1.0, v69
	v_add_f32_e32 v71, 1.0, v71
	v_add_f32_e32 v78, 1.0, v78
	v_add_f32_e32 v79, 1.0, v79
	v_add_f32_e32 v74, 1.0, v74
	v_add_f32_e32 v75, 1.0, v75
	v_rcp_f32_e32 v69, v69
	v_rcp_f32_e32 v71, v71
	v_rcp_f32_e32 v78, v78
	v_rcp_f32_e32 v79, v79
	v_add_f32_e32 v80, 1.0, v80
	v_add_f32_e32 v81, 1.0, v81
	v_rcp_f32_e32 v74, v74
	v_rcp_f32_e32 v75, v75
	v_rcp_f32_e32 v80, v80
	v_rcp_f32_e32 v81, v81
	v_mul_f32_e32 v68, v68, v69
	v_mul_f32_e32 v69, v70, v71
	v_mul_f32_e32 v70, v72, v78
	v_mul_f32_e32 v71, v73, v79
	v_mul_f32_e32 v72, v66, v74
	v_mul_f32_e32 v73, v67, v75
	v_cvt_pkrtz_f16_f32 v66, v68, v69
	v_cvt_pkrtz_f16_f32 v67, v70, v71
	v_mul_f32_e32 v69, v76, v86
	v_mul_f32_e32 v70, v77, v87
	v_mul_f32_e32 v69, v69, v80
	v_mul_f32_e32 v70, v70, v81
	v_cvt_pkrtz_f16_f32 v68, v72, v73
	v_cvt_pkrtz_f16_f32 v69, v69, v70
	global_store_dwordx4 v[82:83], v[66:69], off nt
	s_nop 1
	v_mov_b32_e32 v66, v195
	v_add_u32_e32 v67, 0x80, v146
	v_mad_i64_i32 v[68:69], s[8:9], v67, s58, v[114:115]
	v_lshl_add_u64 v[68:69], v[68:69], 0, v[116:117]
	v_pk_mul_f32 v[64:65], v[64:65], v[66:67] op_sel_hi:[1,0]
	v_pk_mul_f32 v[62:63], v[62:63], v[66:67] op_sel_hi:[1,0]
	v_pk_mul_f32 v[60:61], v[60:61], v[66:67] op_sel_hi:[1,0]
	v_pk_mul_f32 v[58:59], v[58:59], v[66:67] op_sel_hi:[1,0]
	v_pk_mul_f32 v[56:57], v[56:57], v[66:67] op_sel_hi:[1,0]
	v_pk_mul_f32 v[54:55], v[54:55], v[66:67] op_sel_hi:[1,0]
	v_pk_mul_f32 v[52:53], v[52:53], v[66:67] op_sel_hi:[1,0]
	v_pk_mul_f32 v[50:51], v[50:51], v[66:67] op_sel_hi:[1,0]
	v_mul_f32_e32 v54, v62, v54
	v_mul_f32_e32 v62, 0xbfb8aa3b, v62
	v_mul_f32_e32 v55, v63, v55
	v_mul_f32_e32 v63, 0xbfb8aa3b, v63
	v_mul_f32_e32 v56, v64, v56
	v_mul_f32_e32 v64, 0xbfb8aa3b, v64
	v_mul_f32_e32 v57, v65, v57
	v_mul_f32_e32 v65, 0xbfb8aa3b, v65
	v_mul_f32_e32 v50, v58, v50
	v_mul_f32_e32 v58, 0xbfb8aa3b, v58
	v_mul_f32_e32 v51, v59, v51
	v_mul_f32_e32 v59, 0xbfb8aa3b, v59
	v_mul_f32_e32 v52, v60, v52
	v_mul_f32_e32 v60, 0xbfb8aa3b, v60
	v_mul_f32_e32 v53, v61, v53
	v_mul_f32_e32 v61, 0xbfb8aa3b, v61
	v_exp_f32_e32 v62, v62
	v_exp_f32_e32 v63, v63
	v_exp_f32_e32 v64, v64
	v_exp_f32_e32 v65, v65
	v_exp_f32_e32 v58, v58
	v_exp_f32_e32 v59, v59
	v_exp_f32_e32 v60, v60
	v_exp_f32_e32 v61, v61
	v_add_f32_e32 v62, 1.0, v62
	v_add_f32_e32 v63, 1.0, v63
	v_add_f32_e32 v64, 1.0, v64
	v_add_f32_e32 v65, 1.0, v65
	v_add_f32_e32 v58, 1.0, v58
	v_add_f32_e32 v59, 1.0, v59
	v_add_f32_e32 v60, 1.0, v60
	v_add_f32_e32 v61, 1.0, v61
	v_rcp_f32_e32 v62, v62
	v_rcp_f32_e32 v63, v63
	v_rcp_f32_e32 v64, v64
	v_rcp_f32_e32 v65, v65
	v_rcp_f32_e32 v58, v58
	v_rcp_f32_e32 v59, v59
	v_rcp_f32_e32 v60, v60
	v_rcp_f32_e32 v61, v61
	v_mul_f32_e32 v54, v54, v62
	v_mul_f32_e32 v55, v55, v63
	v_mul_f32_e32 v56, v56, v64
	v_mul_f32_e32 v57, v57, v65
	v_mul_f32_e32 v58, v50, v58
	v_mul_f32_e32 v59, v51, v59
	v_mul_f32_e32 v60, v52, v60
	v_mul_f32_e32 v53, v53, v61
	v_cvt_pkrtz_f16_f32 v50, v54, v55
	v_cvt_pkrtz_f16_f32 v51, v56, v57
	v_cvt_pkrtz_f16_f32 v52, v58, v59
	v_cvt_pkrtz_f16_f32 v53, v60, v53
	global_store_dwordx4 v[68:69], v[50:53], off nt
	s_nop 1
	v_mov_b32_e32 v50, v196
	v_add_u32_e32 v51, 0x90, v146
	v_mad_i64_i32 v[52:53], s[8:9], v51, s58, v[114:115]
	v_lshl_add_u64 v[52:53], v[52:53], 0, v[116:117]
	v_pk_mul_f32 v[48:49], v[48:49], v[50:51] op_sel_hi:[1,0]
	v_pk_mul_f32 v[46:47], v[46:47], v[50:51] op_sel_hi:[1,0]
	v_pk_mul_f32 v[44:45], v[44:45], v[50:51] op_sel_hi:[1,0]
	v_pk_mul_f32 v[42:43], v[42:43], v[50:51] op_sel_hi:[1,0]
	v_pk_mul_f32 v[40:41], v[40:41], v[50:51] op_sel_hi:[1,0]
	v_pk_mul_f32 v[38:39], v[38:39], v[50:51] op_sel_hi:[1,0]
	v_pk_mul_f32 v[36:37], v[36:37], v[50:51] op_sel_hi:[1,0]
	v_pk_mul_f32 v[34:35], v[34:35], v[50:51] op_sel_hi:[1,0]
	v_mul_f32_e32 v38, v46, v38
	v_mul_f32_e32 v46, 0xbfb8aa3b, v46
	v_mul_f32_e32 v39, v47, v39
	v_mul_f32_e32 v47, 0xbfb8aa3b, v47
	v_mul_f32_e32 v40, v48, v40
	v_mul_f32_e32 v48, 0xbfb8aa3b, v48
	v_mul_f32_e32 v41, v49, v41
	v_mul_f32_e32 v49, 0xbfb8aa3b, v49
	v_mul_f32_e32 v34, v42, v34
	v_mul_f32_e32 v42, 0xbfb8aa3b, v42
	v_mul_f32_e32 v35, v43, v35
	v_mul_f32_e32 v43, 0xbfb8aa3b, v43
	v_mul_f32_e32 v36, v44, v36
	v_mul_f32_e32 v44, 0xbfb8aa3b, v44
	v_mul_f32_e32 v37, v45, v37
	v_mul_f32_e32 v45, 0xbfb8aa3b, v45
	v_exp_f32_e32 v46, v46
	v_exp_f32_e32 v47, v47
	v_exp_f32_e32 v48, v48
	v_exp_f32_e32 v49, v49
	v_exp_f32_e32 v42, v42
	v_exp_f32_e32 v43, v43
	v_exp_f32_e32 v44, v44
	v_exp_f32_e32 v45, v45
	v_add_f32_e32 v46, 1.0, v46
	v_add_f32_e32 v47, 1.0, v47
	v_add_f32_e32 v48, 1.0, v48
	v_add_f32_e32 v49, 1.0, v49
	v_add_f32_e32 v42, 1.0, v42
	v_add_f32_e32 v43, 1.0, v43
	v_add_f32_e32 v44, 1.0, v44
	v_add_f32_e32 v45, 1.0, v45
	v_rcp_f32_e32 v46, v46
	v_rcp_f32_e32 v47, v47
	v_rcp_f32_e32 v48, v48
	v_rcp_f32_e32 v49, v49
	v_rcp_f32_e32 v42, v42
	v_rcp_f32_e32 v43, v43
	v_rcp_f32_e32 v44, v44
	v_rcp_f32_e32 v45, v45
	v_mul_f32_e32 v38, v38, v46
	v_mul_f32_e32 v39, v39, v47
	v_mul_f32_e32 v40, v40, v48
	v_mul_f32_e32 v41, v41, v49
	v_mul_f32_e32 v42, v34, v42
	v_mul_f32_e32 v43, v35, v43
	v_mul_f32_e32 v44, v36, v44
	v_mul_f32_e32 v37, v37, v45
	v_cvt_pkrtz_f16_f32 v34, v38, v39
	v_cvt_pkrtz_f16_f32 v35, v40, v41
	v_cvt_pkrtz_f16_f32 v36, v42, v43
	v_cvt_pkrtz_f16_f32 v37, v44, v37
	global_store_dwordx4 v[52:53], v[34:37], off nt
	s_nop 1
	v_mov_b32_e32 v34, v197
	v_add_u32_e32 v35, 0xa0, v146
	v_mad_i64_i32 v[36:37], s[8:9], v35, s58, v[114:115]
	v_lshl_add_u64 v[36:37], v[36:37], 0, v[116:117]
	v_pk_mul_f32 v[32:33], v[32:33], v[34:35] op_sel_hi:[1,0]
	v_pk_mul_f32 v[30:31], v[30:31], v[34:35] op_sel_hi:[1,0]
	v_pk_mul_f32 v[28:29], v[28:29], v[34:35] op_sel_hi:[1,0]
	v_pk_mul_f32 v[26:27], v[26:27], v[34:35] op_sel_hi:[1,0]
	v_pk_mul_f32 v[24:25], v[24:25], v[34:35] op_sel_hi:[1,0]
	v_pk_mul_f32 v[22:23], v[22:23], v[34:35] op_sel_hi:[1,0]
	v_pk_mul_f32 v[20:21], v[20:21], v[34:35] op_sel_hi:[1,0]
	v_pk_mul_f32 v[18:19], v[18:19], v[34:35] op_sel_hi:[1,0]
	v_mul_f32_e32 v22, v30, v22
	v_mul_f32_e32 v30, 0xbfb8aa3b, v30
	v_mul_f32_e32 v23, v31, v23
	v_mul_f32_e32 v31, 0xbfb8aa3b, v31
	v_mul_f32_e32 v24, v32, v24
	v_mul_f32_e32 v32, 0xbfb8aa3b, v32
	v_mul_f32_e32 v25, v33, v25
	v_mul_f32_e32 v33, 0xbfb8aa3b, v33
	v_mul_f32_e32 v18, v26, v18
	v_mul_f32_e32 v26, 0xbfb8aa3b, v26
	v_mul_f32_e32 v19, v27, v19
	v_mul_f32_e32 v27, 0xbfb8aa3b, v27
	v_mul_f32_e32 v20, v28, v20
	v_mul_f32_e32 v28, 0xbfb8aa3b, v28
	v_mul_f32_e32 v21, v29, v21
	v_mul_f32_e32 v29, 0xbfb8aa3b, v29
	v_exp_f32_e32 v30, v30
	v_exp_f32_e32 v31, v31
	v_exp_f32_e32 v32, v32
	v_exp_f32_e32 v33, v33
	v_exp_f32_e32 v26, v26
	v_exp_f32_e32 v27, v27
	v_exp_f32_e32 v28, v28
	v_exp_f32_e32 v29, v29
	v_add_f32_e32 v30, 1.0, v30
	v_add_f32_e32 v31, 1.0, v31
	v_add_f32_e32 v32, 1.0, v32
	v_add_f32_e32 v33, 1.0, v33
	v_add_f32_e32 v26, 1.0, v26
	v_add_f32_e32 v27, 1.0, v27
	v_add_f32_e32 v28, 1.0, v28
	v_add_f32_e32 v29, 1.0, v29
	v_rcp_f32_e32 v30, v30
	v_rcp_f32_e32 v31, v31
	v_rcp_f32_e32 v32, v32
	v_rcp_f32_e32 v33, v33
	v_rcp_f32_e32 v26, v26
	v_rcp_f32_e32 v27, v27
	v_rcp_f32_e32 v28, v28
	v_rcp_f32_e32 v29, v29
	v_mul_f32_e32 v22, v22, v30
	v_mul_f32_e32 v23, v23, v31
	v_mul_f32_e32 v24, v24, v32
	v_mul_f32_e32 v25, v25, v33
	v_mul_f32_e32 v26, v18, v26
	v_mul_f32_e32 v27, v19, v27
	v_mul_f32_e32 v28, v20, v28
	v_mul_f32_e32 v21, v21, v29
	v_cvt_pkrtz_f16_f32 v18, v22, v23
	v_cvt_pkrtz_f16_f32 v19, v24, v25
	v_cvt_pkrtz_f16_f32 v20, v26, v27
	v_cvt_pkrtz_f16_f32 v21, v28, v21
	global_store_dwordx4 v[36:37], v[18:21], off nt
	s_nop 1
	v_mov_b32_e32 v18, v198
	v_add_u32_e32 v19, 0xb0, v146
	v_mad_i64_i32 v[20:21], s[8:9], v19, s58, v[114:115]
	v_lshl_add_u64 v[20:21], v[20:21], 0, v[116:117]
	v_pk_mul_f32 v[16:17], v[16:17], v[18:19] op_sel_hi:[1,0]
	v_pk_mul_f32 v[14:15], v[14:15], v[18:19] op_sel_hi:[1,0]
	v_pk_mul_f32 v[12:13], v[12:13], v[18:19] op_sel_hi:[1,0]
	v_pk_mul_f32 v[10:11], v[10:11], v[18:19] op_sel_hi:[1,0]
	v_pk_mul_f32 v[8:9], v[8:9], v[18:19] op_sel_hi:[1,0]
	v_pk_mul_f32 v[6:7], v[6:7], v[18:19] op_sel_hi:[1,0]
	v_pk_mul_f32 v[4:5], v[4:5], v[18:19] op_sel_hi:[1,0]
	v_pk_mul_f32 v[2:3], v[2:3], v[18:19] op_sel_hi:[1,0]
	v_mul_f32_e32 v6, v14, v6
	v_mul_f32_e32 v14, 0xbfb8aa3b, v14
	v_mul_f32_e32 v7, v15, v7
	v_mul_f32_e32 v15, 0xbfb8aa3b, v15
	v_mul_f32_e32 v8, v16, v8
	v_mul_f32_e32 v16, 0xbfb8aa3b, v16
	v_mul_f32_e32 v9, v17, v9
	v_mul_f32_e32 v17, 0xbfb8aa3b, v17
	v_mul_f32_e32 v2, v10, v2
	v_mul_f32_e32 v10, 0xbfb8aa3b, v10
	v_mul_f32_e32 v3, v11, v3
	v_mul_f32_e32 v11, 0xbfb8aa3b, v11
	v_mul_f32_e32 v4, v12, v4
	v_mul_f32_e32 v12, 0xbfb8aa3b, v12
	v_mul_f32_e32 v5, v13, v5
	v_mul_f32_e32 v13, 0xbfb8aa3b, v13
	v_exp_f32_e32 v14, v14
	v_exp_f32_e32 v15, v15
	v_exp_f32_e32 v16, v16
	v_exp_f32_e32 v17, v17
	v_exp_f32_e32 v10, v10
	v_exp_f32_e32 v11, v11
	v_exp_f32_e32 v12, v12
	v_exp_f32_e32 v13, v13
	v_add_f32_e32 v14, 1.0, v14
	v_add_f32_e32 v15, 1.0, v15
	v_add_f32_e32 v16, 1.0, v16
	v_add_f32_e32 v17, 1.0, v17
	v_add_f32_e32 v10, 1.0, v10
	v_add_f32_e32 v11, 1.0, v11
	v_add_f32_e32 v12, 1.0, v12
	v_add_f32_e32 v13, 1.0, v13
	v_rcp_f32_e32 v14, v14
	v_rcp_f32_e32 v15, v15
	v_rcp_f32_e32 v16, v16
	v_rcp_f32_e32 v17, v17
	v_rcp_f32_e32 v10, v10
	v_rcp_f32_e32 v11, v11
	v_rcp_f32_e32 v12, v12
	v_rcp_f32_e32 v13, v13
	v_mul_f32_e32 v6, v6, v14
	v_mul_f32_e32 v7, v7, v15
	v_mul_f32_e32 v8, v8, v16
	v_mul_f32_e32 v9, v9, v17
	v_mul_f32_e32 v10, v2, v10
	v_mul_f32_e32 v11, v3, v11
	v_mul_f32_e32 v12, v4, v12
	v_mul_f32_e32 v5, v5, v13
	v_cvt_pkrtz_f16_f32 v2, v6, v7
	v_cvt_pkrtz_f16_f32 v3, v8, v9
	v_cvt_pkrtz_f16_f32 v4, v10, v11
	v_cvt_pkrtz_f16_f32 v5, v12, v5
	global_store_dwordx4 v[20:21], v[2:5], off nt
	s_cbranch_vccnz .LBB0_1011
	s_andn2_b64 vcc, exec, s[0:1]
	s_cbranch_vccnz .LBB0_1010
	s_barrier
	s_branch .LBB0_1010
